# v40 + WABST heavy path rewritten (bk rows staged via LDS, 8 interleaved accumulators)
# speedup vs baseline: 1.0221x; 1.0138x over previous
.LBB0_184:
	s_and_b64 vcc, exec, s[12:13]
	s_cbranch_vccz .LBB0_179
	s_lshl_b32 s14, s14, 6
	s_lshl_b32 s12, s15, 3
	s_ashr_i32 s15, s14, 31
	s_lshl_b64 s[14:15], s[14:15], 2
	s_add_u32 s21, s8, s14
	s_addc_u32 s22, s9, s15
	s_ashr_i32 s13, s12, 31
	s_lshl_b64 s[14:15], s[12:13], 12
	s_add_u32 s14, s21, s14
	s_addc_u32 s15, s22, s15
	v_lshrrev_b32_e32 v156, 3, v66
	v_and_b32_e32 v157, 7, v66
	v_lshlrev_b32_e32 v156, 12, v156
	v_lshl_or_b32 v156, v157, 5, v156
	global_load_dwordx4 v[144:147], v156, s[14:15]
	global_load_dwordx4 v[148:151], v156, s[14:15] offset:16
	v_mov_b32_e32 v152, v50
	v_mov_b32_e32 v153, v51
	global_load_dwordx4 v[2:5], v[152:153], off offset:0
	global_load_dwordx4 v[6:9], v[152:153], off offset:16
	global_load_dwordx4 v[10:13], v[152:153], off offset:32
	global_load_dwordx4 v[14:17], v[152:153], off offset:48
	global_load_dwordx4 v[18:21], v[152:153], off offset:64
	global_load_dwordx4 v[22:25], v[152:153], off offset:80
	global_load_dwordx4 v[26:29], v[152:153], off offset:96
	global_load_dwordx4 v[30:33], v[152:153], off offset:112
	global_load_dwordx4 v[34:37], v[152:153], off offset:128
	global_load_dwordx4 v[38:41], v[152:153], off offset:144
	global_load_dwordx4 v[42:45], v[152:153], off offset:160
	global_load_dwordx4 v[46:49], v[152:153], off offset:176
	global_load_dwordx4 v[50:53], v[152:153], off offset:192
	global_load_dwordx4 v[54:57], v[152:153], off offset:208
	global_load_dwordx4 v[58:61], v[152:153], off offset:224
	global_load_dwordx4 v[62:65], v[152:153], off offset:240
	v_lshrrev_b32_e32 v155, 6, v210
	v_mul_u32_u24_e32 v155, 0x4100, v155
	v_lshl_add_u32 v154, v66, 5, v155
	s_waitcnt vmcnt(16)
	ds_write_b128 v154, v[144:147]
	ds_write_b128 v154, v[148:151] offset:16
	ds_read_b128 v[80:83], v155 offset:0
	ds_read_b128 v[84:87], v155 offset:256
	ds_read_b128 v[88:91], v155 offset:512
	ds_read_b128 v[92:95], v155 offset:768
	ds_read_b128 v[96:99], v155 offset:1024
	ds_read_b128 v[100:103], v155 offset:1280
	ds_read_b128 v[104:107], v155 offset:1536
	ds_read_b128 v[108:111], v155 offset:1792
	s_waitcnt vmcnt(0)
	s_waitcnt lgkmcnt(7)
	v_fma_f32 v72, v2, v80, 0
	v_fmac_f32_e32 v72, v3, v81
	v_fmac_f32_e32 v72, v4, v82
	v_fmac_f32_e32 v72, v5, v83
	ds_read_b128 v[112:115], v155 offset:16
	s_waitcnt lgkmcnt(7)
	v_fma_f32 v73, v2, v84, 0
	v_fmac_f32_e32 v73, v3, v85
	v_fmac_f32_e32 v73, v4, v86
	v_fmac_f32_e32 v73, v5, v87
	ds_read_b128 v[116:119], v155 offset:272
	s_waitcnt lgkmcnt(7)
	v_fma_f32 v74, v2, v88, 0
	v_fmac_f32_e32 v74, v3, v89
	v_fmac_f32_e32 v74, v4, v90
	v_fmac_f32_e32 v74, v5, v91
	ds_read_b128 v[120:123], v155 offset:528
	s_waitcnt lgkmcnt(7)
	v_fma_f32 v75, v2, v92, 0
	v_fmac_f32_e32 v75, v3, v93
	v_fmac_f32_e32 v75, v4, v94
	v_fmac_f32_e32 v75, v5, v95
	ds_read_b128 v[124:127], v155 offset:784
	s_waitcnt lgkmcnt(7)
	v_fma_f32 v76, v2, v96, 0
	v_fmac_f32_e32 v76, v3, v97
	v_fmac_f32_e32 v76, v4, v98
	v_fmac_f32_e32 v76, v5, v99
	ds_read_b128 v[128:131], v155 offset:1040
	s_waitcnt lgkmcnt(7)
	v_fma_f32 v77, v2, v100, 0
	v_fmac_f32_e32 v77, v3, v101
	v_fmac_f32_e32 v77, v4, v102
	v_fmac_f32_e32 v77, v5, v103
	ds_read_b128 v[132:135], v155 offset:1296
	s_waitcnt lgkmcnt(7)
	v_fma_f32 v78, v2, v104, 0
	v_fmac_f32_e32 v78, v3, v105
	v_fmac_f32_e32 v78, v4, v106
	v_fmac_f32_e32 v78, v5, v107
	ds_read_b128 v[136:139], v155 offset:1552
	s_waitcnt lgkmcnt(7)
	v_fma_f32 v79, v2, v108, 0
	v_fmac_f32_e32 v79, v3, v109
	v_fmac_f32_e32 v79, v4, v110
	v_fmac_f32_e32 v79, v5, v111
	ds_read_b128 v[140:143], v155 offset:1808
	s_waitcnt lgkmcnt(7)
	v_fmac_f32_e32 v72, v6, v112
	v_fmac_f32_e32 v72, v7, v113
	v_fmac_f32_e32 v72, v8, v114
	v_fmac_f32_e32 v72, v9, v115
	ds_read_b128 v[80:83], v155 offset:32
	s_waitcnt lgkmcnt(7)
	v_fmac_f32_e32 v73, v6, v116
	v_fmac_f32_e32 v73, v7, v117
	v_fmac_f32_e32 v73, v8, v118
	v_fmac_f32_e32 v73, v9, v119
	ds_read_b128 v[84:87], v155 offset:288
	s_waitcnt lgkmcnt(7)
	v_fmac_f32_e32 v74, v6, v120
	v_fmac_f32_e32 v74, v7, v121
	v_fmac_f32_e32 v74, v8, v122
	v_fmac_f32_e32 v74, v9, v123
	ds_read_b128 v[88:91], v155 offset:544
	s_waitcnt lgkmcnt(7)
	v_fmac_f32_e32 v75, v6, v124
	v_fmac_f32_e32 v75, v7, v125
	v_fmac_f32_e32 v75, v8, v126
	v_fmac_f32_e32 v75, v9, v127
	ds_read_b128 v[92:95], v155 offset:800
	s_waitcnt lgkmcnt(7)
	v_fmac_f32_e32 v76, v6, v128
	v_fmac_f32_e32 v76, v7, v129
	v_fmac_f32_e32 v76, v8, v130
	v_fmac_f32_e32 v76, v9, v131
	ds_read_b128 v[96:99], v155 offset:1056
	s_waitcnt lgkmcnt(7)
	v_fmac_f32_e32 v77, v6, v132
	v_fmac_f32_e32 v77, v7, v133
	v_fmac_f32_e32 v77, v8, v134
	v_fmac_f32_e32 v77, v9, v135
	ds_read_b128 v[100:103], v155 offset:1312
	s_waitcnt lgkmcnt(7)
	v_fmac_f32_e32 v78, v6, v136
	v_fmac_f32_e32 v78, v7, v137
	v_fmac_f32_e32 v78, v8, v138
	v_fmac_f32_e32 v78, v9, v139
	ds_read_b128 v[104:107], v155 offset:1568
	s_waitcnt lgkmcnt(7)
	v_fmac_f32_e32 v79, v6, v140
	v_fmac_f32_e32 v79, v7, v141
	v_fmac_f32_e32 v79, v8, v142
	v_fmac_f32_e32 v79, v9, v143
	ds_read_b128 v[108:111], v155 offset:1824
	s_waitcnt lgkmcnt(7)
	v_fmac_f32_e32 v72, v10, v80
	v_fmac_f32_e32 v72, v11, v81
	v_fmac_f32_e32 v72, v12, v82
	v_fmac_f32_e32 v72, v13, v83
	ds_read_b128 v[112:115], v155 offset:48
	s_waitcnt lgkmcnt(7)
	v_fmac_f32_e32 v73, v10, v84
	v_fmac_f32_e32 v73, v11, v85
	v_fmac_f32_e32 v73, v12, v86
	v_fmac_f32_e32 v73, v13, v87
	ds_read_b128 v[116:119], v155 offset:304
	s_waitcnt lgkmcnt(7)
	v_fmac_f32_e32 v74, v10, v88
	v_fmac_f32_e32 v74, v11, v89
	v_fmac_f32_e32 v74, v12, v90
	v_fmac_f32_e32 v74, v13, v91
	ds_read_b128 v[120:123], v155 offset:560
	s_waitcnt lgkmcnt(7)
	v_fmac_f32_e32 v75, v10, v92
	v_fmac_f32_e32 v75, v11, v93
	v_fmac_f32_e32 v75, v12, v94
	v_fmac_f32_e32 v75, v13, v95
	ds_read_b128 v[124:127], v155 offset:816
	s_waitcnt lgkmcnt(7)
	v_fmac_f32_e32 v76, v10, v96
	v_fmac_f32_e32 v76, v11, v97
	v_fmac_f32_e32 v76, v12, v98
	v_fmac_f32_e32 v76, v13, v99
	ds_read_b128 v[128:131], v155 offset:1072
	s_waitcnt lgkmcnt(7)
	v_fmac_f32_e32 v77, v10, v100
	v_fmac_f32_e32 v77, v11, v101
	v_fmac_f32_e32 v77, v12, v102
	v_fmac_f32_e32 v77, v13, v103
	ds_read_b128 v[132:135], v155 offset:1328
	s_waitcnt lgkmcnt(7)
	v_fmac_f32_e32 v78, v10, v104
	v_fmac_f32_e32 v78, v11, v105
	v_fmac_f32_e32 v78, v12, v106
	v_fmac_f32_e32 v78, v13, v107
	ds_read_b128 v[136:139], v155 offset:1584
	s_waitcnt lgkmcnt(7)
	v_fmac_f32_e32 v79, v10, v108
	v_fmac_f32_e32 v79, v11, v109
	v_fmac_f32_e32 v79, v12, v110
	v_fmac_f32_e32 v79, v13, v111
	ds_read_b128 v[140:143], v155 offset:1840
	s_waitcnt lgkmcnt(7)
	v_fmac_f32_e32 v72, v14, v112
	v_fmac_f32_e32 v72, v15, v113
	v_fmac_f32_e32 v72, v16, v114
	v_fmac_f32_e32 v72, v17, v115
	ds_read_b128 v[80:83], v155 offset:64
	s_waitcnt lgkmcnt(7)
	v_fmac_f32_e32 v73, v14, v116
	v_fmac_f32_e32 v73, v15, v117
	v_fmac_f32_e32 v73, v16, v118
	v_fmac_f32_e32 v73, v17, v119
	ds_read_b128 v[84:87], v155 offset:320
	s_waitcnt lgkmcnt(7)
	v_fmac_f32_e32 v74, v14, v120
	v_fmac_f32_e32 v74, v15, v121
	v_fmac_f32_e32 v74, v16, v122
	v_fmac_f32_e32 v74, v17, v123
	ds_read_b128 v[88:91], v155 offset:576
	s_waitcnt lgkmcnt(7)
	v_fmac_f32_e32 v75, v14, v124
	v_fmac_f32_e32 v75, v15, v125
	v_fmac_f32_e32 v75, v16, v126
	v_fmac_f32_e32 v75, v17, v127
	ds_read_b128 v[92:95], v155 offset:832
	s_waitcnt lgkmcnt(7)
	v_fmac_f32_e32 v76, v14, v128
	v_fmac_f32_e32 v76, v15, v129
	v_fmac_f32_e32 v76, v16, v130
	v_fmac_f32_e32 v76, v17, v131
	ds_read_b128 v[96:99], v155 offset:1088
	s_waitcnt lgkmcnt(7)
	v_fmac_f32_e32 v77, v14, v132
	v_fmac_f32_e32 v77, v15, v133
	v_fmac_f32_e32 v77, v16, v134
	v_fmac_f32_e32 v77, v17, v135
	ds_read_b128 v[100:103], v155 offset:1344
	s_waitcnt lgkmcnt(7)
	v_fmac_f32_e32 v78, v14, v136
	v_fmac_f32_e32 v78, v15, v137
	v_fmac_f32_e32 v78, v16, v138
	v_fmac_f32_e32 v78, v17, v139
	ds_read_b128 v[104:107], v155 offset:1600
	s_waitcnt lgkmcnt(7)
	v_fmac_f32_e32 v79, v14, v140
	v_fmac_f32_e32 v79, v15, v141
	v_fmac_f32_e32 v79, v16, v142
	v_fmac_f32_e32 v79, v17, v143
	ds_read_b128 v[108:111], v155 offset:1856
	s_waitcnt lgkmcnt(7)
	v_fmac_f32_e32 v72, v18, v80
	v_fmac_f32_e32 v72, v19, v81
	v_fmac_f32_e32 v72, v20, v82
	v_fmac_f32_e32 v72, v21, v83
	ds_read_b128 v[112:115], v155 offset:80
	s_waitcnt lgkmcnt(7)
	v_fmac_f32_e32 v73, v18, v84
	v_fmac_f32_e32 v73, v19, v85
	v_fmac_f32_e32 v73, v20, v86
	v_fmac_f32_e32 v73, v21, v87
	ds_read_b128 v[116:119], v155 offset:336
	s_waitcnt lgkmcnt(7)
	v_fmac_f32_e32 v74, v18, v88
	v_fmac_f32_e32 v74, v19, v89
	v_fmac_f32_e32 v74, v20, v90
	v_fmac_f32_e32 v74, v21, v91
	ds_read_b128 v[120:123], v155 offset:592
	s_waitcnt lgkmcnt(7)
	v_fmac_f32_e32 v75, v18, v92
	v_fmac_f32_e32 v75, v19, v93
	v_fmac_f32_e32 v75, v20, v94
	v_fmac_f32_e32 v75, v21, v95
	ds_read_b128 v[124:127], v155 offset:848
	s_waitcnt lgkmcnt(7)
	v_fmac_f32_e32 v76, v18, v96
	v_fmac_f32_e32 v76, v19, v97
	v_fmac_f32_e32 v76, v20, v98
	v_fmac_f32_e32 v76, v21, v99
	ds_read_b128 v[128:131], v155 offset:1104
	s_waitcnt lgkmcnt(7)
	v_fmac_f32_e32 v77, v18, v100
	v_fmac_f32_e32 v77, v19, v101
	v_fmac_f32_e32 v77, v20, v102
	v_fmac_f32_e32 v77, v21, v103
	ds_read_b128 v[132:135], v155 offset:1360
	s_waitcnt lgkmcnt(7)
	v_fmac_f32_e32 v78, v18, v104
	v_fmac_f32_e32 v78, v19, v105
	v_fmac_f32_e32 v78, v20, v106
	v_fmac_f32_e32 v78, v21, v107
	ds_read_b128 v[136:139], v155 offset:1616
	s_waitcnt lgkmcnt(7)
	v_fmac_f32_e32 v79, v18, v108
	v_fmac_f32_e32 v79, v19, v109
	v_fmac_f32_e32 v79, v20, v110
	v_fmac_f32_e32 v79, v21, v111
	ds_read_b128 v[140:143], v155 offset:1872
	s_waitcnt lgkmcnt(7)
	v_fmac_f32_e32 v72, v22, v112
	v_fmac_f32_e32 v72, v23, v113
	v_fmac_f32_e32 v72, v24, v114
	v_fmac_f32_e32 v72, v25, v115
	ds_read_b128 v[80:83], v155 offset:96
	s_waitcnt lgkmcnt(7)
	v_fmac_f32_e32 v73, v22, v116
	v_fmac_f32_e32 v73, v23, v117
	v_fmac_f32_e32 v73, v24, v118
	v_fmac_f32_e32 v73, v25, v119
	ds_read_b128 v[84:87], v155 offset:352
	s_waitcnt lgkmcnt(7)
	v_fmac_f32_e32 v74, v22, v120
	v_fmac_f32_e32 v74, v23, v121
	v_fmac_f32_e32 v74, v24, v122
	v_fmac_f32_e32 v74, v25, v123
	ds_read_b128 v[88:91], v155 offset:608
	s_waitcnt lgkmcnt(7)
	v_fmac_f32_e32 v75, v22, v124
	v_fmac_f32_e32 v75, v23, v125
	v_fmac_f32_e32 v75, v24, v126
	v_fmac_f32_e32 v75, v25, v127
	ds_read_b128 v[92:95], v155 offset:864
	s_waitcnt lgkmcnt(7)
	v_fmac_f32_e32 v76, v22, v128
	v_fmac_f32_e32 v76, v23, v129
	v_fmac_f32_e32 v76, v24, v130
	v_fmac_f32_e32 v76, v25, v131
	ds_read_b128 v[96:99], v155 offset:1120
	s_waitcnt lgkmcnt(7)
	v_fmac_f32_e32 v77, v22, v132
	v_fmac_f32_e32 v77, v23, v133
	v_fmac_f32_e32 v77, v24, v134
	v_fmac_f32_e32 v77, v25, v135
	ds_read_b128 v[100:103], v155 offset:1376
	s_waitcnt lgkmcnt(7)
	v_fmac_f32_e32 v78, v22, v136
	v_fmac_f32_e32 v78, v23, v137
	v_fmac_f32_e32 v78, v24, v138
	v_fmac_f32_e32 v78, v25, v139
	ds_read_b128 v[104:107], v155 offset:1632
	s_waitcnt lgkmcnt(7)
	v_fmac_f32_e32 v79, v22, v140
	v_fmac_f32_e32 v79, v23, v141
	v_fmac_f32_e32 v79, v24, v142
	v_fmac_f32_e32 v79, v25, v143
	ds_read_b128 v[108:111], v155 offset:1888
	s_waitcnt lgkmcnt(7)
	v_fmac_f32_e32 v72, v26, v80
	v_fmac_f32_e32 v72, v27, v81
	v_fmac_f32_e32 v72, v28, v82
	v_fmac_f32_e32 v72, v29, v83
	ds_read_b128 v[112:115], v155 offset:112
	s_waitcnt lgkmcnt(7)
	v_fmac_f32_e32 v73, v26, v84
	v_fmac_f32_e32 v73, v27, v85
	v_fmac_f32_e32 v73, v28, v86
	v_fmac_f32_e32 v73, v29, v87
	ds_read_b128 v[116:119], v155 offset:368
	s_waitcnt lgkmcnt(7)
	v_fmac_f32_e32 v74, v26, v88
	v_fmac_f32_e32 v74, v27, v89
	v_fmac_f32_e32 v74, v28, v90
	v_fmac_f32_e32 v74, v29, v91
	ds_read_b128 v[120:123], v155 offset:624
	s_waitcnt lgkmcnt(7)
	v_fmac_f32_e32 v75, v26, v92
	v_fmac_f32_e32 v75, v27, v93
	v_fmac_f32_e32 v75, v28, v94
	v_fmac_f32_e32 v75, v29, v95
	ds_read_b128 v[124:127], v155 offset:880
	s_waitcnt lgkmcnt(7)
	v_fmac_f32_e32 v76, v26, v96
	v_fmac_f32_e32 v76, v27, v97
	v_fmac_f32_e32 v76, v28, v98
	v_fmac_f32_e32 v76, v29, v99
	ds_read_b128 v[128:131], v155 offset:1136
	s_waitcnt lgkmcnt(7)
	v_fmac_f32_e32 v77, v26, v100
	v_fmac_f32_e32 v77, v27, v101
	v_fmac_f32_e32 v77, v28, v102
	v_fmac_f32_e32 v77, v29, v103
	ds_read_b128 v[132:135], v155 offset:1392
	s_waitcnt lgkmcnt(7)
	v_fmac_f32_e32 v78, v26, v104
	v_fmac_f32_e32 v78, v27, v105
	v_fmac_f32_e32 v78, v28, v106
	v_fmac_f32_e32 v78, v29, v107
	ds_read_b128 v[136:139], v155 offset:1648
	s_waitcnt lgkmcnt(7)
	v_fmac_f32_e32 v79, v26, v108
	v_fmac_f32_e32 v79, v27, v109
	v_fmac_f32_e32 v79, v28, v110
	v_fmac_f32_e32 v79, v29, v111
	ds_read_b128 v[140:143], v155 offset:1904
	s_waitcnt lgkmcnt(7)
	v_fmac_f32_e32 v72, v30, v112
	v_fmac_f32_e32 v72, v31, v113
	v_fmac_f32_e32 v72, v32, v114
	v_fmac_f32_e32 v72, v33, v115
	ds_read_b128 v[80:83], v155 offset:128
	s_waitcnt lgkmcnt(7)
	v_fmac_f32_e32 v73, v30, v116
	v_fmac_f32_e32 v73, v31, v117
	v_fmac_f32_e32 v73, v32, v118
	v_fmac_f32_e32 v73, v33, v119
	ds_read_b128 v[84:87], v155 offset:384
	s_waitcnt lgkmcnt(7)
	v_fmac_f32_e32 v74, v30, v120
	v_fmac_f32_e32 v74, v31, v121
	v_fmac_f32_e32 v74, v32, v122
	v_fmac_f32_e32 v74, v33, v123
	ds_read_b128 v[88:91], v155 offset:640
	s_waitcnt lgkmcnt(7)
	v_fmac_f32_e32 v75, v30, v124
	v_fmac_f32_e32 v75, v31, v125
	v_fmac_f32_e32 v75, v32, v126
	v_fmac_f32_e32 v75, v33, v127
	ds_read_b128 v[92:95], v155 offset:896
	s_waitcnt lgkmcnt(7)
	v_fmac_f32_e32 v76, v30, v128
	v_fmac_f32_e32 v76, v31, v129
	v_fmac_f32_e32 v76, v32, v130
	v_fmac_f32_e32 v76, v33, v131
	ds_read_b128 v[96:99], v155 offset:1152
	s_waitcnt lgkmcnt(7)
	v_fmac_f32_e32 v77, v30, v132
	v_fmac_f32_e32 v77, v31, v133
	v_fmac_f32_e32 v77, v32, v134
	v_fmac_f32_e32 v77, v33, v135
	ds_read_b128 v[100:103], v155 offset:1408
	s_waitcnt lgkmcnt(7)
	v_fmac_f32_e32 v78, v30, v136
	v_fmac_f32_e32 v78, v31, v137
	v_fmac_f32_e32 v78, v32, v138
	v_fmac_f32_e32 v78, v33, v139
	ds_read_b128 v[104:107], v155 offset:1664
	s_waitcnt lgkmcnt(7)
	v_fmac_f32_e32 v79, v30, v140
	v_fmac_f32_e32 v79, v31, v141
	v_fmac_f32_e32 v79, v32, v142
	v_fmac_f32_e32 v79, v33, v143
	ds_read_b128 v[108:111], v155 offset:1920
	s_waitcnt lgkmcnt(7)
	v_fmac_f32_e32 v72, v34, v80
	v_fmac_f32_e32 v72, v35, v81
	v_fmac_f32_e32 v72, v36, v82
	v_fmac_f32_e32 v72, v37, v83
	ds_read_b128 v[112:115], v155 offset:144
	s_waitcnt lgkmcnt(7)
	v_fmac_f32_e32 v73, v34, v84
	v_fmac_f32_e32 v73, v35, v85
	v_fmac_f32_e32 v73, v36, v86
	v_fmac_f32_e32 v73, v37, v87
	ds_read_b128 v[116:119], v155 offset:400
	s_waitcnt lgkmcnt(7)
	v_fmac_f32_e32 v74, v34, v88
	v_fmac_f32_e32 v74, v35, v89
	v_fmac_f32_e32 v74, v36, v90
	v_fmac_f32_e32 v74, v37, v91
	ds_read_b128 v[120:123], v155 offset:656
	s_waitcnt lgkmcnt(7)
	v_fmac_f32_e32 v75, v34, v92
	v_fmac_f32_e32 v75, v35, v93
	v_fmac_f32_e32 v75, v36, v94
	v_fmac_f32_e32 v75, v37, v95
	ds_read_b128 v[124:127], v155 offset:912
	s_waitcnt lgkmcnt(7)
	v_fmac_f32_e32 v76, v34, v96
	v_fmac_f32_e32 v76, v35, v97
	v_fmac_f32_e32 v76, v36, v98
	v_fmac_f32_e32 v76, v37, v99
	ds_read_b128 v[128:131], v155 offset:1168
	s_waitcnt lgkmcnt(7)
	v_fmac_f32_e32 v77, v34, v100
	v_fmac_f32_e32 v77, v35, v101
	v_fmac_f32_e32 v77, v36, v102
	v_fmac_f32_e32 v77, v37, v103
	ds_read_b128 v[132:135], v155 offset:1424
	s_waitcnt lgkmcnt(7)
	v_fmac_f32_e32 v78, v34, v104
	v_fmac_f32_e32 v78, v35, v105
	v_fmac_f32_e32 v78, v36, v106
	v_fmac_f32_e32 v78, v37, v107
	ds_read_b128 v[136:139], v155 offset:1680
	s_waitcnt lgkmcnt(7)
	v_fmac_f32_e32 v79, v34, v108
	v_fmac_f32_e32 v79, v35, v109
	v_fmac_f32_e32 v79, v36, v110
	v_fmac_f32_e32 v79, v37, v111
	ds_read_b128 v[140:143], v155 offset:1936
	s_waitcnt lgkmcnt(7)
	v_fmac_f32_e32 v72, v38, v112
	v_fmac_f32_e32 v72, v39, v113
	v_fmac_f32_e32 v72, v40, v114
	v_fmac_f32_e32 v72, v41, v115
	ds_read_b128 v[80:83], v155 offset:160
	s_waitcnt lgkmcnt(7)
	v_fmac_f32_e32 v73, v38, v116
	v_fmac_f32_e32 v73, v39, v117
	v_fmac_f32_e32 v73, v40, v118
	v_fmac_f32_e32 v73, v41, v119
	ds_read_b128 v[84:87], v155 offset:416
	s_waitcnt lgkmcnt(7)
	v_fmac_f32_e32 v74, v38, v120
	v_fmac_f32_e32 v74, v39, v121
	v_fmac_f32_e32 v74, v40, v122
	v_fmac_f32_e32 v74, v41, v123
	ds_read_b128 v[88:91], v155 offset:672
	s_waitcnt lgkmcnt(7)
	v_fmac_f32_e32 v75, v38, v124
	v_fmac_f32_e32 v75, v39, v125
	v_fmac_f32_e32 v75, v40, v126
	v_fmac_f32_e32 v75, v41, v127
	ds_read_b128 v[92:95], v155 offset:928
	s_waitcnt lgkmcnt(7)
	v_fmac_f32_e32 v76, v38, v128
	v_fmac_f32_e32 v76, v39, v129
	v_fmac_f32_e32 v76, v40, v130
	v_fmac_f32_e32 v76, v41, v131
	ds_read_b128 v[96:99], v155 offset:1184
	s_waitcnt lgkmcnt(7)
	v_fmac_f32_e32 v77, v38, v132
	v_fmac_f32_e32 v77, v39, v133
	v_fmac_f32_e32 v77, v40, v134
	v_fmac_f32_e32 v77, v41, v135
	ds_read_b128 v[100:103], v155 offset:1440
	s_waitcnt lgkmcnt(7)
	v_fmac_f32_e32 v78, v38, v136
	v_fmac_f32_e32 v78, v39, v137
	v_fmac_f32_e32 v78, v40, v138
	v_fmac_f32_e32 v78, v41, v139
	ds_read_b128 v[104:107], v155 offset:1696
	s_waitcnt lgkmcnt(7)
	v_fmac_f32_e32 v79, v38, v140
	v_fmac_f32_e32 v79, v39, v141
	v_fmac_f32_e32 v79, v40, v142
	v_fmac_f32_e32 v79, v41, v143
	ds_read_b128 v[108:111], v155 offset:1952
	s_waitcnt lgkmcnt(7)
	v_fmac_f32_e32 v72, v42, v80
	v_fmac_f32_e32 v72, v43, v81
	v_fmac_f32_e32 v72, v44, v82
	v_fmac_f32_e32 v72, v45, v83
	ds_read_b128 v[112:115], v155 offset:176
	s_waitcnt lgkmcnt(7)
	v_fmac_f32_e32 v73, v42, v84
	v_fmac_f32_e32 v73, v43, v85
	v_fmac_f32_e32 v73, v44, v86
	v_fmac_f32_e32 v73, v45, v87
	ds_read_b128 v[116:119], v155 offset:432
	s_waitcnt lgkmcnt(7)
	v_fmac_f32_e32 v74, v42, v88
	v_fmac_f32_e32 v74, v43, v89
	v_fmac_f32_e32 v74, v44, v90
	v_fmac_f32_e32 v74, v45, v91
	ds_read_b128 v[120:123], v155 offset:688
	s_waitcnt lgkmcnt(7)
	v_fmac_f32_e32 v75, v42, v92
	v_fmac_f32_e32 v75, v43, v93
	v_fmac_f32_e32 v75, v44, v94
	v_fmac_f32_e32 v75, v45, v95
	ds_read_b128 v[124:127], v155 offset:944
	s_waitcnt lgkmcnt(7)
	v_fmac_f32_e32 v76, v42, v96
	v_fmac_f32_e32 v76, v43, v97
	v_fmac_f32_e32 v76, v44, v98
	v_fmac_f32_e32 v76, v45, v99
	ds_read_b128 v[128:131], v155 offset:1200
	s_waitcnt lgkmcnt(7)
	v_fmac_f32_e32 v77, v42, v100
	v_fmac_f32_e32 v77, v43, v101
	v_fmac_f32_e32 v77, v44, v102
	v_fmac_f32_e32 v77, v45, v103
	ds_read_b128 v[132:135], v155 offset:1456
	s_waitcnt lgkmcnt(7)
	v_fmac_f32_e32 v78, v42, v104
	v_fmac_f32_e32 v78, v43, v105
	v_fmac_f32_e32 v78, v44, v106
	v_fmac_f32_e32 v78, v45, v107
	ds_read_b128 v[136:139], v155 offset:1712
	s_waitcnt lgkmcnt(7)
	v_fmac_f32_e32 v79, v42, v108
	v_fmac_f32_e32 v79, v43, v109
	v_fmac_f32_e32 v79, v44, v110
	v_fmac_f32_e32 v79, v45, v111
	ds_read_b128 v[140:143], v155 offset:1968
	s_waitcnt lgkmcnt(7)
	v_fmac_f32_e32 v72, v46, v112
	v_fmac_f32_e32 v72, v47, v113
	v_fmac_f32_e32 v72, v48, v114
	v_fmac_f32_e32 v72, v49, v115
	ds_read_b128 v[80:83], v155 offset:192
	s_waitcnt lgkmcnt(7)
	v_fmac_f32_e32 v73, v46, v116
	v_fmac_f32_e32 v73, v47, v117
	v_fmac_f32_e32 v73, v48, v118
	v_fmac_f32_e32 v73, v49, v119
	ds_read_b128 v[84:87], v155 offset:448
	s_waitcnt lgkmcnt(7)
	v_fmac_f32_e32 v74, v46, v120
	v_fmac_f32_e32 v74, v47, v121
	v_fmac_f32_e32 v74, v48, v122
	v_fmac_f32_e32 v74, v49, v123
	ds_read_b128 v[88:91], v155 offset:704
	s_waitcnt lgkmcnt(7)
	v_fmac_f32_e32 v75, v46, v124
	v_fmac_f32_e32 v75, v47, v125
	v_fmac_f32_e32 v75, v48, v126
	v_fmac_f32_e32 v75, v49, v127
	ds_read_b128 v[92:95], v155 offset:960
	s_waitcnt lgkmcnt(7)
	v_fmac_f32_e32 v76, v46, v128
	v_fmac_f32_e32 v76, v47, v129
	v_fmac_f32_e32 v76, v48, v130
	v_fmac_f32_e32 v76, v49, v131
	ds_read_b128 v[96:99], v155 offset:1216
	s_waitcnt lgkmcnt(7)
	v_fmac_f32_e32 v77, v46, v132
	v_fmac_f32_e32 v77, v47, v133
	v_fmac_f32_e32 v77, v48, v134
	v_fmac_f32_e32 v77, v49, v135
	ds_read_b128 v[100:103], v155 offset:1472
	s_waitcnt lgkmcnt(7)
	v_fmac_f32_e32 v78, v46, v136
	v_fmac_f32_e32 v78, v47, v137
	v_fmac_f32_e32 v78, v48, v138
	v_fmac_f32_e32 v78, v49, v139
	ds_read_b128 v[104:107], v155 offset:1728
	s_waitcnt lgkmcnt(7)
	v_fmac_f32_e32 v79, v46, v140
	v_fmac_f32_e32 v79, v47, v141
	v_fmac_f32_e32 v79, v48, v142
	v_fmac_f32_e32 v79, v49, v143
	ds_read_b128 v[108:111], v155 offset:1984
	s_waitcnt lgkmcnt(7)
	v_fmac_f32_e32 v72, v50, v80
	v_fmac_f32_e32 v72, v51, v81
	v_fmac_f32_e32 v72, v52, v82
	v_fmac_f32_e32 v72, v53, v83
	ds_read_b128 v[112:115], v155 offset:208
	s_waitcnt lgkmcnt(7)
	v_fmac_f32_e32 v73, v50, v84
	v_fmac_f32_e32 v73, v51, v85
	v_fmac_f32_e32 v73, v52, v86
	v_fmac_f32_e32 v73, v53, v87
	ds_read_b128 v[116:119], v155 offset:464
	s_waitcnt lgkmcnt(7)
	v_fmac_f32_e32 v74, v50, v88
	v_fmac_f32_e32 v74, v51, v89
	v_fmac_f32_e32 v74, v52, v90
	v_fmac_f32_e32 v74, v53, v91
	ds_read_b128 v[120:123], v155 offset:720
	s_waitcnt lgkmcnt(7)
	v_fmac_f32_e32 v75, v50, v92
	v_fmac_f32_e32 v75, v51, v93
	v_fmac_f32_e32 v75, v52, v94
	v_fmac_f32_e32 v75, v53, v95
	ds_read_b128 v[124:127], v155 offset:976
	s_waitcnt lgkmcnt(7)
	v_fmac_f32_e32 v76, v50, v96
	v_fmac_f32_e32 v76, v51, v97
	v_fmac_f32_e32 v76, v52, v98
	v_fmac_f32_e32 v76, v53, v99
	ds_read_b128 v[128:131], v155 offset:1232
	s_waitcnt lgkmcnt(7)
	v_fmac_f32_e32 v77, v50, v100
	v_fmac_f32_e32 v77, v51, v101
	v_fmac_f32_e32 v77, v52, v102
	v_fmac_f32_e32 v77, v53, v103
	ds_read_b128 v[132:135], v155 offset:1488
	s_waitcnt lgkmcnt(7)
	v_fmac_f32_e32 v78, v50, v104
	v_fmac_f32_e32 v78, v51, v105
	v_fmac_f32_e32 v78, v52, v106
	v_fmac_f32_e32 v78, v53, v107
	ds_read_b128 v[136:139], v155 offset:1744
	s_waitcnt lgkmcnt(7)
	v_fmac_f32_e32 v79, v50, v108
	v_fmac_f32_e32 v79, v51, v109
	v_fmac_f32_e32 v79, v52, v110
	v_fmac_f32_e32 v79, v53, v111
	ds_read_b128 v[140:143], v155 offset:2000
	s_waitcnt lgkmcnt(7)
	v_fmac_f32_e32 v72, v54, v112
	v_fmac_f32_e32 v72, v55, v113
	v_fmac_f32_e32 v72, v56, v114
	v_fmac_f32_e32 v72, v57, v115
	ds_read_b128 v[80:83], v155 offset:224
	s_waitcnt lgkmcnt(7)
	v_fmac_f32_e32 v73, v54, v116
	v_fmac_f32_e32 v73, v55, v117
	v_fmac_f32_e32 v73, v56, v118
	v_fmac_f32_e32 v73, v57, v119
	ds_read_b128 v[84:87], v155 offset:480
	s_waitcnt lgkmcnt(7)
	v_fmac_f32_e32 v74, v54, v120
	v_fmac_f32_e32 v74, v55, v121
	v_fmac_f32_e32 v74, v56, v122
	v_fmac_f32_e32 v74, v57, v123
	ds_read_b128 v[88:91], v155 offset:736
	s_waitcnt lgkmcnt(7)
	v_fmac_f32_e32 v75, v54, v124
	v_fmac_f32_e32 v75, v55, v125
	v_fmac_f32_e32 v75, v56, v126
	v_fmac_f32_e32 v75, v57, v127
	ds_read_b128 v[92:95], v155 offset:992
	s_waitcnt lgkmcnt(7)
	v_fmac_f32_e32 v76, v54, v128
	v_fmac_f32_e32 v76, v55, v129
	v_fmac_f32_e32 v76, v56, v130
	v_fmac_f32_e32 v76, v57, v131
	ds_read_b128 v[96:99], v155 offset:1248
	s_waitcnt lgkmcnt(7)
	v_fmac_f32_e32 v77, v54, v132
	v_fmac_f32_e32 v77, v55, v133
	v_fmac_f32_e32 v77, v56, v134
	v_fmac_f32_e32 v77, v57, v135
	ds_read_b128 v[100:103], v155 offset:1504
	s_waitcnt lgkmcnt(7)
	v_fmac_f32_e32 v78, v54, v136
	v_fmac_f32_e32 v78, v55, v137
	v_fmac_f32_e32 v78, v56, v138
	v_fmac_f32_e32 v78, v57, v139
	ds_read_b128 v[104:107], v155 offset:1760
	s_waitcnt lgkmcnt(7)
	v_fmac_f32_e32 v79, v54, v140
	v_fmac_f32_e32 v79, v55, v141
	v_fmac_f32_e32 v79, v56, v142
	v_fmac_f32_e32 v79, v57, v143
	ds_read_b128 v[108:111], v155 offset:2016
	s_waitcnt lgkmcnt(7)
	v_fmac_f32_e32 v72, v58, v80
	v_fmac_f32_e32 v72, v59, v81
	v_fmac_f32_e32 v72, v60, v82
	v_fmac_f32_e32 v72, v61, v83
	ds_read_b128 v[112:115], v155 offset:240
	s_waitcnt lgkmcnt(7)
	v_fmac_f32_e32 v73, v58, v84
	v_fmac_f32_e32 v73, v59, v85
	v_fmac_f32_e32 v73, v60, v86
	v_fmac_f32_e32 v73, v61, v87
	ds_read_b128 v[116:119], v155 offset:496
	s_waitcnt lgkmcnt(7)
	v_fmac_f32_e32 v74, v58, v88
	v_fmac_f32_e32 v74, v59, v89
	v_fmac_f32_e32 v74, v60, v90
	v_fmac_f32_e32 v74, v61, v91
	ds_read_b128 v[120:123], v155 offset:752
	s_waitcnt lgkmcnt(7)
	v_fmac_f32_e32 v75, v58, v92
	v_fmac_f32_e32 v75, v59, v93
	v_fmac_f32_e32 v75, v60, v94
	v_fmac_f32_e32 v75, v61, v95
	ds_read_b128 v[124:127], v155 offset:1008
	s_waitcnt lgkmcnt(7)
	v_fmac_f32_e32 v76, v58, v96
	v_fmac_f32_e32 v76, v59, v97
	v_fmac_f32_e32 v76, v60, v98
	v_fmac_f32_e32 v76, v61, v99
	ds_read_b128 v[128:131], v155 offset:1264
	s_waitcnt lgkmcnt(7)
	v_fmac_f32_e32 v77, v58, v100
	v_fmac_f32_e32 v77, v59, v101
	v_fmac_f32_e32 v77, v60, v102
	v_fmac_f32_e32 v77, v61, v103
	ds_read_b128 v[132:135], v155 offset:1520
	s_waitcnt lgkmcnt(7)
	v_fmac_f32_e32 v78, v58, v104
	v_fmac_f32_e32 v78, v59, v105
	v_fmac_f32_e32 v78, v60, v106
	v_fmac_f32_e32 v78, v61, v107
	ds_read_b128 v[136:139], v155 offset:1776
	s_waitcnt lgkmcnt(7)
	v_fmac_f32_e32 v79, v58, v108
	v_fmac_f32_e32 v79, v59, v109
	v_fmac_f32_e32 v79, v60, v110
	v_fmac_f32_e32 v79, v61, v111
	ds_read_b128 v[140:143], v155 offset:2032
	s_waitcnt lgkmcnt(7)
	v_fmac_f32_e32 v72, v62, v112
	v_fmac_f32_e32 v72, v63, v113
	v_fmac_f32_e32 v72, v64, v114
	v_fmac_f32_e32 v72, v65, v115
	s_waitcnt lgkmcnt(6)
	v_fmac_f32_e32 v73, v62, v116
	v_fmac_f32_e32 v73, v63, v117
	v_fmac_f32_e32 v73, v64, v118
	v_fmac_f32_e32 v73, v65, v119
	s_waitcnt lgkmcnt(5)
	v_fmac_f32_e32 v74, v62, v120
	v_fmac_f32_e32 v74, v63, v121
	v_fmac_f32_e32 v74, v64, v122
	v_fmac_f32_e32 v74, v65, v123
	s_waitcnt lgkmcnt(4)
	v_fmac_f32_e32 v75, v62, v124
	v_fmac_f32_e32 v75, v63, v125
	v_fmac_f32_e32 v75, v64, v126
	v_fmac_f32_e32 v75, v65, v127
	s_waitcnt lgkmcnt(3)
	v_fmac_f32_e32 v76, v62, v128
	v_fmac_f32_e32 v76, v63, v129
	v_fmac_f32_e32 v76, v64, v130
	v_fmac_f32_e32 v76, v65, v131
	s_waitcnt lgkmcnt(2)
	v_fmac_f32_e32 v77, v62, v132
	v_fmac_f32_e32 v77, v63, v133
	v_fmac_f32_e32 v77, v64, v134
	v_fmac_f32_e32 v77, v65, v135
	s_waitcnt lgkmcnt(1)
	v_fmac_f32_e32 v78, v62, v136
	v_fmac_f32_e32 v78, v63, v137
	v_fmac_f32_e32 v78, v64, v138
	v_fmac_f32_e32 v78, v65, v139
	s_waitcnt lgkmcnt(0)
	v_fmac_f32_e32 v79, v62, v140
	v_fmac_f32_e32 v79, v63, v141
	v_fmac_f32_e32 v79, v64, v142
	v_fmac_f32_e32 v79, v65, v143
	s_add_i32 s13, s12, s20
	s_add_i32 s13, s13, 0
	v_mul_f32_e32 v72, v68, v72
	v_mad_i64_i32 v[156:157], s[16:17], s13, v1, v[70:71]
	v_cvt_pk_bf16_f32 v72, v72, v72
	global_store_short v[156:157], v72, off
	s_add_i32 s13, s12, s20
	s_add_i32 s13, s13, 1
	v_mul_f32_e32 v73, v68, v73
	v_mad_i64_i32 v[156:157], s[16:17], s13, v1, v[70:71]
	v_cvt_pk_bf16_f32 v73, v73, v73
	global_store_short v[156:157], v73, off
	s_add_i32 s13, s12, s20
	s_add_i32 s13, s13, 2
	v_mul_f32_e32 v74, v68, v74
	v_mad_i64_i32 v[156:157], s[16:17], s13, v1, v[70:71]
	v_cvt_pk_bf16_f32 v74, v74, v74
	global_store_short v[156:157], v74, off
	s_add_i32 s13, s12, s20
	s_add_i32 s13, s13, 3
	v_mul_f32_e32 v75, v68, v75
	v_mad_i64_i32 v[156:157], s[16:17], s13, v1, v[70:71]
	v_cvt_pk_bf16_f32 v75, v75, v75
	global_store_short v[156:157], v75, off
	s_add_i32 s13, s12, s20
	s_add_i32 s13, s13, 4
	v_mul_f32_e32 v76, v68, v76
	v_mad_i64_i32 v[156:157], s[16:17], s13, v1, v[70:71]
	v_cvt_pk_bf16_f32 v76, v76, v76
	global_store_short v[156:157], v76, off
	s_add_i32 s13, s12, s20
	s_add_i32 s13, s13, 5
	v_mul_f32_e32 v77, v68, v77
	v_mad_i64_i32 v[156:157], s[16:17], s13, v1, v[70:71]
	v_cvt_pk_bf16_f32 v77, v77, v77
	global_store_short v[156:157], v77, off
	s_add_i32 s13, s12, s20
	s_add_i32 s13, s13, 6
	v_mul_f32_e32 v78, v68, v78
	v_mad_i64_i32 v[156:157], s[16:17], s13, v1, v[70:71]
	v_cvt_pk_bf16_f32 v78, v78, v78
	global_store_short v[156:157], v78, off
	s_add_i32 s13, s12, s20
	s_add_i32 s13, s13, 7
	v_mul_f32_e32 v79, v68, v79
	v_mad_i64_i32 v[156:157], s[16:17], s13, v1, v[70:71]
	v_cvt_pk_bf16_f32 v79, v79, v79
	global_store_short v[156:157], v79, off
	s_branch .LBB0_179
